# hand-written WO epilogue: all residual loads issued ahead of the stores (on top of DOWN epilogue + LN1 stats)
# speedup vs baseline: 1.0044x; 1.0044x over previous
; #define PG8_STAGE(bufoff, gbase, voff) do { _Pragma("unroll") for (int _i = 0; _i < 2; ++_i) \
;     __builtin_amdgcn_global_load_lds((const unsigned*)((const char*)(gbase) + (voff)[_i]), (LAS unsigned*)(lds + (bufoff) + ldsw + _i * 8192), 16, 0, 0); } while (0)
; #define PG8_LDA(dst, b, h) do { _Pragma("unroll") for (int m = 0; m < 4; ++m) _Pragma("unroll") for (int k = 0; k < 2; ++k) dst[m][k] = *(const LAS bf16x8*)(lds + PG8_SA(b, h) + aoff + m * 2048 + k * 1024); } while (0)
; #define PG8_LDB(dst, b, h) do { _Pragma("unroll") for (int n = 0; n < 2; ++n) _Pragma("unroll") for (int k = 0; k < 2; ++k) dst[n][k] = *(const LAS bf16x8*)(lds + PG8_SB(b, h) + boff + n * 2048 + k * 1024); } while (0)
; #define PG8_MMA(ai, bj, At, Bt) do { __builtin_amdgcn_s_setprio(1); _Pragma("unroll") for (int m = 0; m < 4; ++m) _Pragma("unroll") for (int n = 0; n < 2; ++n) _Pragma("unroll") for (int k = 0; k < 2; ++k) \
;     acc[ai][bj][m][n] = __builtin_amdgcn_mfma_f32_16x16x32_bf16(Bt[n][k], At[m][k], acc[ai][bj][m][n], 0, 0, 0); __builtin_amdgcn_s_setprio(0); } while (0)
; #define PG8_WAIT_V(n) asm volatile("s_waitcnt vmcnt(" #n ")" ::: "memory")
; #define PG8_WAIT_L(n) asm volatile("s_waitcnt lgkmcnt(" #n ")" ::: "memory")
; #define PG8_BAR __builtin_amdgcn_s_barrier()
; #define PG8_SCHED __builtin_amdgcn_sched_barrier(0)
; template <class Epi>
; __device__ __forceinline__ void gemm_phase(LAS unsigned char* lds, const Gemm g, const StaticOrder& S, const Epi& E, int wv0) {
;     ...
;       PG8_LDB(B0, 0, 0); PG8_SCHED; PG8_LDA(At, 0, 0); PG8_STAGE(PG8_SA(1, 1), a1 + hstepA, voffA);
;       PG8_WAIT_L(8); PG8_BAR; PG8_WAIT_L(0); PG8_MMA(0, 0, At, B0); PG8_BAR; PG8_SCHED;
;       PG8_LDB(B1, 0, 1); PG8_STAGE(PG8_SB(0, 0), b2, voffB);
;       PG8_BAR; PG8_WAIT_L(0); PG8_MMA(0, 1, At, B1); PG8_BAR;
;       PG8_LDA(At, 0, 1); PG8_STAGE(PG8_SA(0, 0), a2, voffA);
;       PG8_BAR; PG8_WAIT_L(0); PG8_MMA(1, 0, At, B0); PG8_BAR; PG8_SCHED;
;       PG8_STAGE(PG8_SB(0, 1), b2 + hstepB, voffB);
;       PG8_WAIT_V(6); PG8_BAR; PG8_MMA(1, 1, At, B1); PG8_BAR;
.LBB0_1100:
	s_add_u32 s0, s20, 0xfff80080
	s_addc_u32 s22, s21, -1
	s_add_i32 s50, 0, 0x10000
	v_add_u32_e32 v142, s50, v185
	ds_read_b128 v[130:133], v142
	ds_read_b128 v[134:137], v142 offset:1024
	ds_read_b128 v[138:141], v142 offset:2048
	ds_read_b128 v[142:145], v142 offset:3072
	s_cmp_eq_u32 s49, 28
	s_cselect_b32 s25, s13, s22
	s_cselect_b32 s24, s45, s0
	s_cselect_b32 s23, s11, s48
	s_cselect_b32 s22, s46, s47
	v_lshl_add_u64 v[192:193], s[20:21], 0, v[168:169]
	s_add_i32 m0, s19, 0xc000
	ds_read_b128 v[146:149], v187
	ds_read_b128 v[150:153], v187 offset:1024
	ds_read_b128 v[154:157], v187 offset:2048
	ds_read_b128 v[158:161], v187 offset:3072
	ds_read_b128 v[172:175], v187 offset:4096
	ds_read_b128 v[176:179], v187 offset:5120
	ds_read_b128 v[180:183], v187 offset:6144
	ds_read_b128 v[188:191], v187 offset:7168
	global_load_lds_dwordx4 v[192:193], off
	v_lshl_add_u64 v[192:193], s[20:21], 0, v[170:171]
	s_add_i32 m0, s19, 0xe000
	s_nop 0
	global_load_lds_dwordx4 v[192:193], off
	s_waitcnt lgkmcnt(8)
	s_barrier
	s_waitcnt lgkmcnt(0)
	s_setprio 1
	s_waitcnt lgkmcnt(0)
	v_mfma_f32_16x16x32_bf16 v[126:129], v[130:133], v[146:149], v[126:129]
	v_mfma_f32_16x16x32_bf16 v[122:125], v[138:141], v[146:149], v[122:125]
	v_mfma_f32_16x16x32_bf16 v[118:121], v[130:133], v[154:157], v[118:121]
	v_mfma_f32_16x16x32_bf16 v[114:117], v[138:141], v[154:157], v[114:117]
	v_mfma_f32_16x16x32_bf16 v[92:95], v[130:133], v[172:175], v[92:95]
	v_mfma_f32_16x16x32_bf16 v[88:91], v[138:141], v[172:175], v[88:91]
	v_mfma_f32_16x16x32_bf16 v[84:87], v[130:133], v[180:183], v[84:87]
	v_mfma_f32_16x16x32_bf16 v[76:79], v[138:141], v[180:183], v[76:79]
	v_mfma_f32_16x16x32_bf16 v[126:129], v[134:137], v[150:153], v[126:129]
	v_mfma_f32_16x16x32_bf16 v[122:125], v[142:145], v[150:153], v[122:125]
	v_mfma_f32_16x16x32_bf16 v[118:121], v[134:137], v[158:161], v[118:121]
	v_mfma_f32_16x16x32_bf16 v[114:117], v[142:145], v[158:161], v[114:117]
	v_mfma_f32_16x16x32_bf16 v[92:95], v[134:137], v[176:179], v[92:95]
	v_mfma_f32_16x16x32_bf16 v[88:91], v[142:145], v[176:179], v[88:91]
	v_mfma_f32_16x16x32_bf16 v[84:87], v[134:137], v[188:191], v[84:87]
	v_mfma_f32_16x16x32_bf16 v[76:79], v[142:145], v[188:191], v[76:79]
	s_setprio 0
	s_barrier
	s_add_i32 s0, 0, 0x14000
	s_add_i32 s50, s50, s31
	v_add_u32_e32 v204, s0, v185
	v_lshl_add_u64 v[208:209], s[22:23], 0, v[96:97]
	s_mov_b32 m0, s50
	ds_read_b128 v[192:195], v204
	ds_read_b128 v[196:199], v204 offset:1024
	ds_read_b128 v[200:203], v204 offset:2048
	ds_read_b128 v[204:207], v204 offset:3072
	global_load_lds_dwordx4 v[208:209], off
	v_lshl_add_u64 v[210:211], s[22:23], 0, v[166:167]
	s_add_i32 m0, s50, 0x2000
	s_nop 0
	global_load_lds_dwordx4 v[210:211], off
	s_barrier
	s_waitcnt lgkmcnt(0)
	s_setprio 1
	s_waitcnt lgkmcnt(0)
	v_mfma_f32_16x16x32_bf16 v[110:113], v[192:195], v[146:149], v[110:113]
	v_mfma_f32_16x16x32_bf16 v[106:109], v[200:203], v[146:149], v[106:109]
	v_mfma_f32_16x16x32_bf16 v[102:105], v[192:195], v[154:157], v[102:105]
	v_mfma_f32_16x16x32_bf16 v[98:101], v[200:203], v[154:157], v[98:101]
	v_mfma_f32_16x16x32_bf16 v[80:83], v[192:195], v[172:175], v[80:83]
	v_mfma_f32_16x16x32_bf16 v[72:75], v[200:203], v[172:175], v[72:75]
	v_mfma_f32_16x16x32_bf16 v[68:71], v[192:195], v[180:183], v[68:71]
	v_mfma_f32_16x16x32_bf16 v[64:67], v[200:203], v[180:183], v[64:67]
	v_mfma_f32_16x16x32_bf16 v[110:113], v[196:199], v[150:153], v[110:113]
	v_mfma_f32_16x16x32_bf16 v[106:109], v[204:207], v[150:153], v[106:109]
	v_mfma_f32_16x16x32_bf16 v[102:105], v[196:199], v[158:161], v[102:105]
	v_mfma_f32_16x16x32_bf16 v[98:101], v[204:207], v[158:161], v[98:101]
	v_mfma_f32_16x16x32_bf16 v[80:83], v[196:199], v[176:179], v[80:83]
	v_mfma_f32_16x16x32_bf16 v[72:75], v[204:207], v[176:179], v[72:75]
	v_mfma_f32_16x16x32_bf16 v[68:71], v[196:199], v[188:191], v[68:71]
	v_mfma_f32_16x16x32_bf16 v[64:67], v[204:207], v[188:191], v[64:67]
	s_setprio 0
	s_mov_b32 m0, s19
	v_lshl_add_u64 v[212:213], s[24:25], 0, v[162:163]
	s_barrier
	ds_read_b128 v[146:149], v187 offset:16384
	ds_read_b128 v[150:153], v187 offset:17408
	ds_read_b128 v[154:157], v187 offset:18432
	ds_read_b128 v[158:161], v187 offset:19456
	ds_read_b128 v[172:175], v187 offset:20480
	ds_read_b128 v[176:179], v187 offset:21504
	ds_read_b128 v[180:183], v187 offset:22528
	ds_read_b128 v[188:191], v187 offset:23552
	global_load_lds_dwordx4 v[212:213], off
	v_lshl_add_u64 v[214:215], s[24:25], 0, v[164:165]
	s_mov_b32 m0, s38
	s_nop 0
	global_load_lds_dwordx4 v[214:215], off
	s_barrier
	s_waitcnt lgkmcnt(0)
	s_setprio 1
	s_waitcnt lgkmcnt(0)
	v_mfma_f32_16x16x32_bf16 v[60:63], v[130:133], v[146:149], v[60:63]
	v_mfma_f32_16x16x32_bf16 v[56:59], v[138:141], v[146:149], v[56:59]
	v_mfma_f32_16x16x32_bf16 v[44:47], v[130:133], v[154:157], v[44:47]
	v_mfma_f32_16x16x32_bf16 v[40:43], v[138:141], v[154:157], v[40:43]
	v_mfma_f32_16x16x32_bf16 v[28:31], v[130:133], v[172:175], v[28:31]
	v_mfma_f32_16x16x32_bf16 v[24:27], v[138:141], v[172:175], v[24:27]
	v_mfma_f32_16x16x32_bf16 v[20:23], v[130:133], v[180:183], v[20:23]
	v_mfma_f32_16x16x32_bf16 v[8:11], v[138:141], v[180:183], v[8:11]
	v_mfma_f32_16x16x32_bf16 v[60:63], v[134:137], v[150:153], v[60:63]
	v_mfma_f32_16x16x32_bf16 v[56:59], v[142:145], v[150:153], v[56:59]
	v_mfma_f32_16x16x32_bf16 v[44:47], v[134:137], v[158:161], v[44:47]
	v_mfma_f32_16x16x32_bf16 v[40:43], v[142:145], v[158:161], v[40:43]
	v_mfma_f32_16x16x32_bf16 v[28:31], v[134:137], v[176:179], v[28:31]
	v_mfma_f32_16x16x32_bf16 v[24:27], v[142:145], v[176:179], v[24:27]
	v_mfma_f32_16x16x32_bf16 v[20:23], v[134:137], v[188:191], v[20:23]
	v_mfma_f32_16x16x32_bf16 v[8:11], v[142:145], v[188:191], v[8:11]
	s_setprio 0
	s_barrier
; #define PG8_STAGE(bufoff, gbase, voff) do { _Pragma("unroll") for (int _i = 0; _i < 2; ++_i) \
;     __builtin_amdgcn_global_load_lds((const unsigned*)((const char*)(gbase) + (voff)[_i]), (LAS unsigned*)(lds + (bufoff) + ldsw + _i * 8192), 16, 0, 0); } while (0)
; #define PG8_LDA(dst, b, h) do { _Pragma("unroll") for (int m = 0; m < 4; ++m) _Pragma("unroll") for (int k = 0; k < 2; ++k) dst[m][k] = *(const LAS bf16x8*)(lds + PG8_SA(b, h) + aoff + m * 2048 + k * 1024); } while (0)
; #define PG8_LDB(dst, b, h) do { _Pragma("unroll") for (int n = 0; n < 2; ++n) _Pragma("unroll") for (int k = 0; k < 2; ++k) dst[n][k] = *(const LAS bf16x8*)(lds + PG8_SB(b, h) + boff + n * 2048 + k * 1024); } while (0)
; #define PG8_MMA(ai, bj, At, Bt) do { __builtin_amdgcn_s_setprio(1); _Pragma("unroll") for (int m = 0; m < 4; ++m) _Pragma("unroll") for (int n = 0; n < 2; ++n) _Pragma("unroll") for (int k = 0; k < 2; ++k) \
;     acc[ai][bj][m][n] = __builtin_amdgcn_mfma_f32_16x16x32_bf16(Bt[n][k], At[m][k], acc[ai][bj][m][n], 0, 0, 0); __builtin_amdgcn_s_setprio(0); } while (0)
; #define PG8_WAIT_V(n) asm volatile("s_waitcnt vmcnt(" #n ")" ::: "memory")
; #define PG8_WAIT_L(n) asm volatile("s_waitcnt lgkmcnt(" #n ")" ::: "memory")
; #define PG8_BAR __builtin_amdgcn_s_barrier()
; #define PG8_SCHED __builtin_amdgcn_sched_barrier(0)
; template <class Epi>
; __device__ __forceinline__ void gemm_phase(LAS unsigned char* lds, const Gemm g, const StaticOrder& S, const Epi& E, int wv0) {
;     ...
;       PG8_LDB(B0, 1, 0); PG8_SCHED; PG8_LDA(At, 1, 0); PG8_STAGE(PG8_SA(0, 1), a2 + hstepA, voffA);
;       PG8_WAIT_L(8); PG8_BAR; PG8_WAIT_L(0); PG8_MMA(0, 0, At, B0); PG8_BAR; PG8_SCHED;
;       PG8_LDB(B1, 1, 1); PG8_STAGE(PG8_SB(1, 0), b3, voffB);
;       PG8_BAR; PG8_WAIT_L(0); PG8_MMA(0, 1, At, B1); PG8_BAR;
;       PG8_LDA(At, 1, 1); PG8_STAGE(PG8_SA(1, 0), a3, voffA);
;       PG8_BAR; PG8_WAIT_L(0); PG8_MMA(1, 0, At, B0); PG8_BAR; PG8_SCHED;
;       PG8_STAGE(PG8_SB(1, 1), b3 + hstepB, voffB);
;       PG8_WAIT_V(6); PG8_BAR; PG8_MMA(1, 1, At, B1); PG8_BAR;
	s_add_u32 s50, s22, 0x80000
	s_addc_u32 s51, s23, 0
	s_add_i32 s0, s0, s31
	v_lshl_add_u64 v[130:131], s[50:51], 0, v[96:97]
	s_mov_b32 m0, s0
	s_nop 0
	global_load_lds_dwordx4 v[130:131], off
	v_lshl_add_u64 v[130:131], s[50:51], 0, v[166:167]
	s_add_i32 m0, s0, 0x2000
	s_nop 0
	global_load_lds_dwordx4 v[130:131], off
	s_waitcnt vmcnt(6)
	s_barrier
	s_setprio 1
	v_mfma_f32_16x16x32_bf16 v[52:55], v[192:195], v[146:149], v[52:55]
	v_mfma_f32_16x16x32_bf16 v[48:51], v[200:203], v[146:149], v[48:51]
	v_mfma_f32_16x16x32_bf16 v[36:39], v[192:195], v[154:157], v[36:39]
	v_mfma_f32_16x16x32_bf16 v[32:35], v[200:203], v[154:157], v[32:35]
	v_mfma_f32_16x16x32_bf16 v[16:19], v[192:195], v[172:175], v[16:19]
	v_mfma_f32_16x16x32_bf16 v[12:15], v[200:203], v[172:175], v[12:15]
	v_mfma_f32_16x16x32_bf16 v[4:7], v[192:195], v[180:183], v[4:7]
	v_mfma_f32_16x16x32_bf16 v[0:3], v[200:203], v[180:183], v[0:3]
	v_mfma_f32_16x16x32_bf16 v[52:55], v[196:199], v[150:153], v[52:55]
	v_mfma_f32_16x16x32_bf16 v[48:51], v[204:207], v[150:153], v[48:51]
	v_mfma_f32_16x16x32_bf16 v[36:39], v[196:199], v[158:161], v[36:39]
	v_mfma_f32_16x16x32_bf16 v[32:35], v[204:207], v[158:161], v[32:35]
	v_mfma_f32_16x16x32_bf16 v[16:19], v[196:199], v[176:179], v[16:19]
	v_mfma_f32_16x16x32_bf16 v[12:15], v[204:207], v[176:179], v[12:15]
	v_mfma_f32_16x16x32_bf16 v[4:7], v[196:199], v[188:191], v[4:7]
	v_mfma_f32_16x16x32_bf16 v[0:3], v[204:207], v[188:191], v[0:3]
	s_setprio 0
	s_add_i32 s0, 0, 0x18000
	v_add_u32_e32 v142, s0, v185
	s_barrier
	ds_read_b128 v[130:133], v142
	ds_read_b128 v[134:137], v142 offset:1024
	ds_read_b128 v[138:141], v142 offset:2048
	ds_read_b128 v[142:145], v142 offset:3072
	s_add_u32 s24, s24, 0x80000
	s_addc_u32 s25, s25, 0
	s_mov_b32 m0, s39
	v_lshl_add_u64 v[192:193], s[24:25], 0, v[162:163]
	ds_read_b128 v[146:149], v187 offset:32768
	ds_read_b128 v[150:153], v187 offset:33792
	ds_read_b128 v[154:157], v187 offset:34816
	ds_read_b128 v[158:161], v187 offset:35840
	ds_read_b128 v[172:175], v187 offset:36864
	ds_read_b128 v[176:179], v187 offset:37888
	ds_read_b128 v[180:183], v187 offset:38912
	ds_read_b128 v[188:191], v187 offset:39936
	global_load_lds_dwordx4 v[192:193], off
	v_lshl_add_u64 v[192:193], s[24:25], 0, v[164:165]
	s_mov_b32 m0, s40
	s_nop 0
	global_load_lds_dwordx4 v[192:193], off
	s_waitcnt lgkmcnt(8)
	s_barrier
	s_waitcnt lgkmcnt(0)
	s_setprio 1
	s_waitcnt lgkmcnt(0)
	v_mfma_f32_16x16x32_bf16 v[126:129], v[130:133], v[146:149], v[126:129]
	v_mfma_f32_16x16x32_bf16 v[122:125], v[138:141], v[146:149], v[122:125]
	v_mfma_f32_16x16x32_bf16 v[118:121], v[130:133], v[154:157], v[118:121]
	v_mfma_f32_16x16x32_bf16 v[114:117], v[138:141], v[154:157], v[114:117]
	v_mfma_f32_16x16x32_bf16 v[92:95], v[130:133], v[172:175], v[92:95]
	v_mfma_f32_16x16x32_bf16 v[88:91], v[138:141], v[172:175], v[88:91]
	v_mfma_f32_16x16x32_bf16 v[84:87], v[130:133], v[180:183], v[84:87]
	v_mfma_f32_16x16x32_bf16 v[76:79], v[138:141], v[180:183], v[76:79]
	v_mfma_f32_16x16x32_bf16 v[126:129], v[134:137], v[150:153], v[126:129]
	v_mfma_f32_16x16x32_bf16 v[122:125], v[142:145], v[150:153], v[122:125]
	v_mfma_f32_16x16x32_bf16 v[118:121], v[134:137], v[158:161], v[118:121]
	v_mfma_f32_16x16x32_bf16 v[114:117], v[142:145], v[158:161], v[114:117]
	v_mfma_f32_16x16x32_bf16 v[92:95], v[134:137], v[176:179], v[92:95]
	v_mfma_f32_16x16x32_bf16 v[88:91], v[142:145], v[176:179], v[88:91]
	v_mfma_f32_16x16x32_bf16 v[84:87], v[134:137], v[188:191], v[84:87]
	v_mfma_f32_16x16x32_bf16 v[76:79], v[142:145], v[188:191], v[76:79]
	s_setprio 0
	s_barrier
	s_add_i32 s24, 0, 0x1c000
	s_add_i32 s0, s0, s31
	v_add_u32_e32 v204, s24, v185
	v_lshl_add_u64 v[208:209], v[208:209], 0, s[72:73]
	s_mov_b32 m0, s0
	ds_read_b128 v[192:195], v204
	ds_read_b128 v[196:199], v204 offset:1024
	ds_read_b128 v[200:203], v204 offset:2048
	ds_read_b128 v[204:207], v204 offset:3072
	global_load_lds_dwordx4 v[208:209], off
	v_lshl_add_u64 v[208:209], v[210:211], 0, s[72:73]
	s_add_i32 m0, s0, 0x2000
	s_nop 0
	global_load_lds_dwordx4 v[208:209], off
	s_barrier
	s_waitcnt lgkmcnt(0)
	s_setprio 1
	s_waitcnt lgkmcnt(0)
	v_mfma_f32_16x16x32_bf16 v[110:113], v[192:195], v[146:149], v[110:113]
	v_mfma_f32_16x16x32_bf16 v[106:109], v[200:203], v[146:149], v[106:109]
	v_mfma_f32_16x16x32_bf16 v[102:105], v[192:195], v[154:157], v[102:105]
	v_mfma_f32_16x16x32_bf16 v[98:101], v[200:203], v[154:157], v[98:101]
	v_mfma_f32_16x16x32_bf16 v[80:83], v[192:195], v[172:175], v[80:83]
	v_mfma_f32_16x16x32_bf16 v[72:75], v[200:203], v[172:175], v[72:75]
	v_mfma_f32_16x16x32_bf16 v[68:71], v[192:195], v[180:183], v[68:71]
	v_mfma_f32_16x16x32_bf16 v[64:67], v[200:203], v[180:183], v[64:67]
	v_mfma_f32_16x16x32_bf16 v[110:113], v[196:199], v[150:153], v[110:113]
	v_mfma_f32_16x16x32_bf16 v[106:109], v[204:207], v[150:153], v[106:109]
	v_mfma_f32_16x16x32_bf16 v[102:105], v[196:199], v[158:161], v[102:105]
	v_mfma_f32_16x16x32_bf16 v[98:101], v[204:207], v[158:161], v[98:101]
	v_mfma_f32_16x16x32_bf16 v[80:83], v[196:199], v[176:179], v[80:83]
	v_mfma_f32_16x16x32_bf16 v[72:75], v[204:207], v[176:179], v[72:75]
	v_mfma_f32_16x16x32_bf16 v[68:71], v[196:199], v[188:191], v[68:71]
	v_mfma_f32_16x16x32_bf16 v[64:67], v[204:207], v[188:191], v[64:67]
	s_setprio 0
	s_mov_b32 m0, s41
	v_lshl_add_u64 v[208:209], v[212:213], 0, s[72:73]
	s_barrier
	ds_read_b128 v[146:149], v187 offset:49152
	ds_read_b128 v[150:153], v187 offset:50176
	ds_read_b128 v[154:157], v187 offset:51200
	ds_read_b128 v[158:161], v187 offset:52224
	ds_read_b128 v[172:175], v187 offset:53248
	ds_read_b128 v[176:179], v187 offset:54272
	ds_read_b128 v[180:183], v187 offset:55296
	ds_read_b128 v[188:191], v187 offset:56320
	global_load_lds_dwordx4 v[208:209], off
	v_lshl_add_u64 v[208:209], v[214:215], 0, s[72:73]
	s_mov_b32 m0, s42
	s_nop 0
	global_load_lds_dwordx4 v[208:209], off
	s_barrier
; #define PG8_STAGE(bufoff, gbase, voff) do { _Pragma("unroll") for (int _i = 0; _i < 2; ++_i) \
;     __builtin_amdgcn_global_load_lds((const unsigned*)((const char*)(gbase) + (voff)[_i]), (LAS unsigned*)(lds + (bufoff) + ldsw + _i * 8192), 16, 0, 0); } while (0)
; #define PG8_LDA(dst, b, h) do { _Pragma("unroll") for (int m = 0; m < 4; ++m) _Pragma("unroll") for (int k = 0; k < 2; ++k) dst[m][k] = *(const LAS bf16x8*)(lds + PG8_SA(b, h) + aoff + m * 2048 + k * 1024); } while (0)
; #define PG8_BAR __builtin_amdgcn_s_barrier()
; template <class Epi>
; __device__ __forceinline__ void gemm_phase(LAS unsigned char* lds, const Gemm g, const StaticOrder& S, const Epi& E, int wv0) {
;     ...
;       PG8_LDB(B0, 0, 0); PG8_SCHED; PG8_LDA(At, 0, 0); PG8_STAGE(PG8_SA(1, 1), a1 + hstepA, voffA);
;       PG8_WAIT_L(8); PG8_BAR; PG8_WAIT_L(0); PG8_MMA(0, 0, At, B0); PG8_BAR; PG8_SCHED;
;       PG8_LDB(B1, 0, 1); PG8_STAGE(PG8_SB(0, 0), b2, voffB);
;       PG8_BAR; PG8_WAIT_L(0); PG8_MMA(0, 1, At, B1); PG8_BAR;
;       PG8_LDA(At, 0, 1); PG8_STAGE(PG8_SA(0, 0), a2, voffA);
;       PG8_BAR; PG8_WAIT_L(0); PG8_MMA(1, 0, At, B0); PG8_BAR; PG8_SCHED;
;       PG8_STAGE(PG8_SB(0, 1), b2 + hstepB, voffB);
;       PG8_WAIT_V(6); PG8_BAR; PG8_MMA(1, 1, At, B1); PG8_BAR;
;       PG8_LDB(B0, 1, 0); PG8_SCHED; PG8_LDA(At, 1, 0); PG8_STAGE(PG8_SA(0, 1), a2 + hstepA, voffA);
;       PG8_WAIT_L(8); PG8_BAR; PG8_WAIT_L(0); PG8_MMA(0, 0, At, B0); PG8_BAR; PG8_SCHED;
;       PG8_LDB(B1, 1, 1); PG8_STAGE(PG8_SB(1, 0), b3, voffB);
;       PG8_BAR; PG8_WAIT_L(0); PG8_MMA(0, 1, At, B1); PG8_BAR;
;       PG8_LDA(At, 1, 1); PG8_STAGE(PG8_SA(1, 0), a3, voffA);
;       PG8_BAR; PG8_WAIT_L(0); PG8_MMA(1, 0, At, B0); PG8_BAR; PG8_SCHED;
;       PG8_STAGE(PG8_SB(1, 1), b3 + hstepB, voffB);
;       PG8_WAIT_V(6); PG8_BAR; PG8_MMA(1, 1, At, B1); PG8_BAR;
;   __device__ __forceinline__ void emit(const EpiPre& q0, int row, int col, f32x4 a, f32x4 b, const f32x4 (&hb)[2][2], const float (&hs)[2][4], int ai_, int m_, int bj_) const {
;     ...
;     } else if (MODE == E_RES) {
;       const f32x4 r0 = q.a0, r1 = q.a1;
;       float* o = (float*)e.out + (size_t)row * DM + col;
;       *(f32x4*)o = (f32x4){ALPHA * r0[0] + v[0], ALPHA * r0[1] + v[1], ALPHA * r0[2] + v[2], ALPHA * r0[3] + v[3]};
;       *(f32x4*)(o + 4) = (f32x4){ALPHA * r1[0] + v[4], ALPHA * r1[1] + v[5], ALPHA * r1[2] + v[6], ALPHA * r1[3] + v[7]};
	s_waitcnt lgkmcnt(0)
	s_setprio 1
	s_waitcnt lgkmcnt(0)
	v_mfma_f32_16x16x32_bf16 v[60:63], v[130:133], v[146:149], v[60:63]
	v_mfma_f32_16x16x32_bf16 v[56:59], v[138:141], v[146:149], v[56:59]
	v_mfma_f32_16x16x32_bf16 v[44:47], v[130:133], v[154:157], v[44:47]
	v_mfma_f32_16x16x32_bf16 v[40:43], v[138:141], v[154:157], v[40:43]
	v_mfma_f32_16x16x32_bf16 v[28:31], v[130:133], v[172:175], v[28:31]
	v_mfma_f32_16x16x32_bf16 v[24:27], v[138:141], v[172:175], v[24:27]
	v_mfma_f32_16x16x32_bf16 v[20:23], v[130:133], v[180:183], v[20:23]
	v_mfma_f32_16x16x32_bf16 v[8:11], v[138:141], v[180:183], v[8:11]
	v_mfma_f32_16x16x32_bf16 v[60:63], v[134:137], v[150:153], v[60:63]
	v_mfma_f32_16x16x32_bf16 v[56:59], v[142:145], v[150:153], v[56:59]
	v_mfma_f32_16x16x32_bf16 v[44:47], v[134:137], v[158:161], v[44:47]
	v_mfma_f32_16x16x32_bf16 v[40:43], v[142:145], v[158:161], v[40:43]
	v_mfma_f32_16x16x32_bf16 v[28:31], v[134:137], v[176:179], v[28:31]
	v_mfma_f32_16x16x32_bf16 v[24:27], v[142:145], v[176:179], v[24:27]
	v_mfma_f32_16x16x32_bf16 v[20:23], v[134:137], v[188:191], v[20:23]
	v_mfma_f32_16x16x32_bf16 v[8:11], v[142:145], v[188:191], v[8:11]
	s_setprio 0
	s_barrier
	s_add_u32 s22, s22, 0x80080
	s_addc_u32 s23, s23, 0
	s_add_i32 s0, s24, s31
	v_lshl_add_u64 v[130:131], s[22:23], 0, v[96:97]
	s_mov_b32 m0, s0
	s_nop 0
	global_load_lds_dwordx4 v[130:131], off
	v_lshl_add_u64 v[130:131], s[22:23], 0, v[166:167]
	s_add_i32 m0, s0, 0x2000
	s_nop 0
	global_load_lds_dwordx4 v[130:131], off
	s_waitcnt vmcnt(6)
	s_barrier
	s_setprio 1
	v_mfma_f32_16x16x32_bf16 v[52:55], v[192:195], v[146:149], v[52:55]
	v_mfma_f32_16x16x32_bf16 v[48:51], v[200:203], v[146:149], v[48:51]
	v_mfma_f32_16x16x32_bf16 v[36:39], v[192:195], v[154:157], v[36:39]
	v_mfma_f32_16x16x32_bf16 v[32:35], v[200:203], v[154:157], v[32:35]
	v_mfma_f32_16x16x32_bf16 v[16:19], v[192:195], v[172:175], v[16:19]
	v_mfma_f32_16x16x32_bf16 v[12:15], v[200:203], v[172:175], v[12:15]
	v_mfma_f32_16x16x32_bf16 v[4:7], v[192:195], v[180:183], v[4:7]
	v_mfma_f32_16x16x32_bf16 v[0:3], v[200:203], v[180:183], v[0:3]
	v_mfma_f32_16x16x32_bf16 v[52:55], v[196:199], v[150:153], v[52:55]
	v_mfma_f32_16x16x32_bf16 v[48:51], v[204:207], v[150:153], v[48:51]
	v_mfma_f32_16x16x32_bf16 v[36:39], v[196:199], v[158:161], v[36:39]
	v_mfma_f32_16x16x32_bf16 v[32:35], v[204:207], v[158:161], v[32:35]
	v_mfma_f32_16x16x32_bf16 v[16:19], v[196:199], v[176:179], v[16:19]
	v_mfma_f32_16x16x32_bf16 v[12:15], v[204:207], v[176:179], v[12:15]
	v_mfma_f32_16x16x32_bf16 v[4:7], v[196:199], v[188:191], v[4:7]
	v_mfma_f32_16x16x32_bf16 v[0:3], v[204:207], v[188:191], v[0:3]
	s_setprio 0
	s_add_i32 s49, s49, 2
	s_add_u32 s20, s20, 0x100
	s_addc_u32 s21, s21, 0
	s_add_u32 s47, s47, 0x100
	s_addc_u32 s48, s48, 0
	s_cmp_gt_u32 s49, 29
	s_barrier
	s_cbranch_scc0 .LBB0_1100
	v_lshl_add_u32 v172, s18, 8, v184
	v_lshl_or_b32 v180, s1, 8, v186
	v_lshlrev_b32_e32 v172, 13, v172
	v_lshl_add_u32 v172, v180, 2, v172
	global_load_dwordx4 v[130:133], v172, s[8:9]
	global_load_dwordx4 v[134:137], v172, s[8:9] offset:16
	global_load_dwordx4 v[138:141], v172, s[8:9] offset:512
	global_load_dwordx4 v[142:145], v172, s[8:9] offset:528
	v_add_u32_e32 v173, 0x20000, v172
	global_load_dwordx4 v[146:149], v173, s[8:9]
	global_load_dwordx4 v[150:153], v173, s[8:9] offset:16
	global_load_dwordx4 v[154:157], v173, s[8:9] offset:512
	global_load_dwordx4 v[158:161], v173, s[8:9] offset:528
	v_add_u32_e32 v174, 0x40000, v172
	global_load_dwordx4 v[188:191], v174, s[8:9]
	global_load_dwordx4 v[192:195], v174, s[8:9] offset:16
	global_load_dwordx4 v[196:199], v174, s[8:9] offset:512
	global_load_dwordx4 v[200:203], v174, s[8:9] offset:528
	v_add_u32_e32 v175, 0x60000, v172
	global_load_dwordx4 v[204:207], v175, s[8:9]
	global_load_dwordx4 v[208:211], v175, s[8:9] offset:16
	global_load_dwordx4 v[212:215], v175, s[8:9] offset:512
	global_load_dwordx4 v[216:219], v175, s[8:9] offset:528
	v_add_u32_e32 v176, 0x100000, v172
	v_add_u32_e32 v177, 0x120000, v172
	v_add_u32_e32 v178, 0x140000, v172
	v_add_u32_e32 v179, 0x160000, v172
	s_waitcnt vmcnt(12)
	v_pk_fma_f32 v[126:127], v[130:131], s[90:91], v[126:127] op_sel_hi:[1,0,1]
	v_pk_fma_f32 v[128:129], v[132:133], s[90:91], v[128:129] op_sel_hi:[1,0,1]
	v_pk_fma_f32 v[122:123], v[134:135], s[90:91], v[122:123] op_sel_hi:[1,0,1]
	v_pk_fma_f32 v[124:125], v[136:137], s[90:91], v[124:125] op_sel_hi:[1,0,1]
	v_pk_fma_f32 v[110:111], v[138:139], s[90:91], v[110:111] op_sel_hi:[1,0,1]
	v_pk_fma_f32 v[112:113], v[140:141], s[90:91], v[112:113] op_sel_hi:[1,0,1]
	v_pk_fma_f32 v[106:107], v[142:143], s[90:91], v[106:107] op_sel_hi:[1,0,1]
	v_pk_fma_f32 v[108:109], v[144:145], s[90:91], v[108:109] op_sel_hi:[1,0,1]
	global_load_dwordx4 v[130:133], v176, s[8:9]
	global_load_dwordx4 v[134:137], v176, s[8:9] offset:16
	global_load_dwordx4 v[138:141], v176, s[8:9] offset:512
	global_load_dwordx4 v[142:145], v176, s[8:9] offset:528
	s_waitcnt vmcnt(12)
	v_pk_fma_f32 v[118:119], v[146:147], s[90:91], v[118:119] op_sel_hi:[1,0,1]
	v_pk_fma_f32 v[120:121], v[148:149], s[90:91], v[120:121] op_sel_hi:[1,0,1]
	v_pk_fma_f32 v[114:115], v[150:151], s[90:91], v[114:115] op_sel_hi:[1,0,1]
	v_pk_fma_f32 v[116:117], v[152:153], s[90:91], v[116:117] op_sel_hi:[1,0,1]
	v_pk_fma_f32 v[102:103], v[154:155], s[90:91], v[102:103] op_sel_hi:[1,0,1]
	v_pk_fma_f32 v[104:105], v[156:157], s[90:91], v[104:105] op_sel_hi:[1,0,1]
	v_pk_fma_f32 v[98:99], v[158:159], s[90:91], v[98:99] op_sel_hi:[1,0,1]
	v_pk_fma_f32 v[100:101], v[160:161], s[90:91], v[100:101] op_sel_hi:[1,0,1]
	global_load_dwordx4 v[146:149], v177, s[8:9]
	global_load_dwordx4 v[150:153], v177, s[8:9] offset:16
	global_load_dwordx4 v[154:157], v177, s[8:9] offset:512
	global_load_dwordx4 v[158:161], v177, s[8:9] offset:528
	s_waitcnt vmcnt(12)
;   __device__ __forceinline__ void emit(const EpiPre& q0, int row, int col, f32x4 a, f32x4 b, const f32x4 (&hb)[2][2], const float (&hs)[2][4], int ai_, int m_, int bj_) const {
;     ...
;     } else if (MODE == E_RES) {
;       const f32x4 r0 = q.a0, r1 = q.a1;
;       float* o = (float*)e.out + (size_t)row * DM + col;
;       *(f32x4*)o = (f32x4){ALPHA * r0[0] + v[0], ALPHA * r0[1] + v[1], ALPHA * r0[2] + v[2], ALPHA * r0[3] + v[3]};
;       *(f32x4*)(o + 4) = (f32x4){ALPHA * r1[0] + v[4], ALPHA * r1[1] + v[5], ALPHA * r1[2] + v[6], ALPHA * r1[3] + v[7]};
	v_pk_fma_f32 v[92:93], v[188:189], s[90:91], v[92:93] op_sel_hi:[1,0,1]
	v_pk_fma_f32 v[94:95], v[190:191], s[90:91], v[94:95] op_sel_hi:[1,0,1]
	v_pk_fma_f32 v[88:89], v[192:193], s[90:91], v[88:89] op_sel_hi:[1,0,1]
	v_pk_fma_f32 v[90:91], v[194:195], s[90:91], v[90:91] op_sel_hi:[1,0,1]
	v_pk_fma_f32 v[80:81], v[196:197], s[90:91], v[80:81] op_sel_hi:[1,0,1]
	v_pk_fma_f32 v[82:83], v[198:199], s[90:91], v[82:83] op_sel_hi:[1,0,1]
	v_pk_fma_f32 v[72:73], v[200:201], s[90:91], v[72:73] op_sel_hi:[1,0,1]
	v_pk_fma_f32 v[74:75], v[202:203], s[90:91], v[74:75] op_sel_hi:[1,0,1]
	global_load_dwordx4 v[188:191], v178, s[8:9]
	global_load_dwordx4 v[192:195], v178, s[8:9] offset:16
	global_load_dwordx4 v[196:199], v178, s[8:9] offset:512
	global_load_dwordx4 v[200:203], v178, s[8:9] offset:528
	s_waitcnt vmcnt(12)
	v_pk_fma_f32 v[84:85], v[204:205], s[90:91], v[84:85] op_sel_hi:[1,0,1]
	v_pk_fma_f32 v[86:87], v[206:207], s[90:91], v[86:87] op_sel_hi:[1,0,1]
	v_pk_fma_f32 v[76:77], v[208:209], s[90:91], v[76:77] op_sel_hi:[1,0,1]
	v_pk_fma_f32 v[78:79], v[210:211], s[90:91], v[78:79] op_sel_hi:[1,0,1]
	v_pk_fma_f32 v[68:69], v[212:213], s[90:91], v[68:69] op_sel_hi:[1,0,1]
	v_pk_fma_f32 v[70:71], v[214:215], s[90:91], v[70:71] op_sel_hi:[1,0,1]
	v_pk_fma_f32 v[64:65], v[216:217], s[90:91], v[64:65] op_sel_hi:[1,0,1]
	v_pk_fma_f32 v[66:67], v[218:219], s[90:91], v[66:67] op_sel_hi:[1,0,1]
	global_load_dwordx4 v[204:207], v179, s[8:9]
	global_load_dwordx4 v[208:211], v179, s[8:9] offset:16
	global_load_dwordx4 v[212:215], v179, s[8:9] offset:512
	global_load_dwordx4 v[216:219], v179, s[8:9] offset:528
	global_store_dwordx4 v172, v[126:129], s[6:7]
	global_store_dwordx4 v172, v[122:125], s[6:7] offset:16
	global_store_dwordx4 v172, v[110:113], s[6:7] offset:512
	global_store_dwordx4 v172, v[106:109], s[6:7] offset:528
	global_store_dwordx4 v173, v[118:121], s[6:7]
	global_store_dwordx4 v173, v[114:117], s[6:7] offset:16
	global_store_dwordx4 v173, v[102:105], s[6:7] offset:512
	global_store_dwordx4 v173, v[98:101], s[6:7] offset:528
	global_store_dwordx4 v174, v[92:95], s[6:7]
	global_store_dwordx4 v174, v[88:91], s[6:7] offset:16
	global_store_dwordx4 v174, v[80:83], s[6:7] offset:512
	global_store_dwordx4 v174, v[72:75], s[6:7] offset:528
	global_store_dwordx4 v175, v[84:87], s[6:7]
	global_store_dwordx4 v175, v[76:79], s[6:7] offset:16
	global_store_dwordx4 v175, v[68:71], s[6:7] offset:512
	global_store_dwordx4 v175, v[64:67], s[6:7] offset:528
	s_waitcnt vmcnt(28)
	v_pk_fma_f32 v[60:61], v[130:131], s[90:91], v[60:61] op_sel_hi:[1,0,1]
	v_pk_fma_f32 v[62:63], v[132:133], s[90:91], v[62:63] op_sel_hi:[1,0,1]
	v_pk_fma_f32 v[56:57], v[134:135], s[90:91], v[56:57] op_sel_hi:[1,0,1]
	v_pk_fma_f32 v[58:59], v[136:137], s[90:91], v[58:59] op_sel_hi:[1,0,1]
	v_pk_fma_f32 v[52:53], v[138:139], s[90:91], v[52:53] op_sel_hi:[1,0,1]
	v_pk_fma_f32 v[54:55], v[140:141], s[90:91], v[54:55] op_sel_hi:[1,0,1]
	v_pk_fma_f32 v[48:49], v[142:143], s[90:91], v[48:49] op_sel_hi:[1,0,1]
	v_pk_fma_f32 v[50:51], v[144:145], s[90:91], v[50:51] op_sel_hi:[1,0,1]
	global_store_dwordx4 v176, v[60:63], s[6:7]
	global_store_dwordx4 v176, v[56:59], s[6:7] offset:16
	global_store_dwordx4 v176, v[52:55], s[6:7] offset:512
	global_store_dwordx4 v176, v[48:51], s[6:7] offset:528
	s_waitcnt vmcnt(28)
	v_pk_fma_f32 v[44:45], v[146:147], s[90:91], v[44:45] op_sel_hi:[1,0,1]
	v_pk_fma_f32 v[46:47], v[148:149], s[90:91], v[46:47] op_sel_hi:[1,0,1]
	v_pk_fma_f32 v[40:41], v[150:151], s[90:91], v[40:41] op_sel_hi:[1,0,1]
	v_pk_fma_f32 v[42:43], v[152:153], s[90:91], v[42:43] op_sel_hi:[1,0,1]
	v_pk_fma_f32 v[36:37], v[154:155], s[90:91], v[36:37] op_sel_hi:[1,0,1]
	v_pk_fma_f32 v[38:39], v[156:157], s[90:91], v[38:39] op_sel_hi:[1,0,1]
	v_pk_fma_f32 v[32:33], v[158:159], s[90:91], v[32:33] op_sel_hi:[1,0,1]
	v_pk_fma_f32 v[34:35], v[160:161], s[90:91], v[34:35] op_sel_hi:[1,0,1]
	global_store_dwordx4 v177, v[44:47], s[6:7]
	global_store_dwordx4 v177, v[40:43], s[6:7] offset:16
	global_store_dwordx4 v177, v[36:39], s[6:7] offset:512
	global_store_dwordx4 v177, v[32:35], s[6:7] offset:528
	s_waitcnt vmcnt(28)
	v_pk_fma_f32 v[28:29], v[188:189], s[90:91], v[28:29] op_sel_hi:[1,0,1]
	v_pk_fma_f32 v[30:31], v[190:191], s[90:91], v[30:31] op_sel_hi:[1,0,1]
	v_pk_fma_f32 v[24:25], v[192:193], s[90:91], v[24:25] op_sel_hi:[1,0,1]
	v_pk_fma_f32 v[26:27], v[194:195], s[90:91], v[26:27] op_sel_hi:[1,0,1]
	v_pk_fma_f32 v[16:17], v[196:197], s[90:91], v[16:17] op_sel_hi:[1,0,1]
	v_pk_fma_f32 v[18:19], v[198:199], s[90:91], v[18:19] op_sel_hi:[1,0,1]
	v_pk_fma_f32 v[12:13], v[200:201], s[90:91], v[12:13] op_sel_hi:[1,0,1]
	v_pk_fma_f32 v[14:15], v[202:203], s[90:91], v[14:15] op_sel_hi:[1,0,1]
	global_store_dwordx4 v178, v[28:31], s[6:7]
	global_store_dwordx4 v178, v[24:27], s[6:7] offset:16
	global_store_dwordx4 v178, v[16:19], s[6:7] offset:512
	global_store_dwordx4 v178, v[12:15], s[6:7] offset:528
	s_waitcnt vmcnt(28)
	v_pk_fma_f32 v[20:21], v[204:205], s[90:91], v[20:21] op_sel_hi:[1,0,1]
	v_pk_fma_f32 v[22:23], v[206:207], s[90:91], v[22:23] op_sel_hi:[1,0,1]
	v_pk_fma_f32 v[8:9], v[208:209], s[90:91], v[8:9] op_sel_hi:[1,0,1]
	v_pk_fma_f32 v[10:11], v[210:211], s[90:91], v[10:11] op_sel_hi:[1,0,1]
	v_pk_fma_f32 v[4:5], v[212:213], s[90:91], v[4:5] op_sel_hi:[1,0,1]
	v_pk_fma_f32 v[6:7], v[214:215], s[90:91], v[6:7] op_sel_hi:[1,0,1]
	v_pk_fma_f32 v[0:1], v[216:217], s[90:91], v[0:1] op_sel_hi:[1,0,1]
	v_pk_fma_f32 v[2:3], v[218:219], s[90:91], v[2:3] op_sel_hi:[1,0,1]
	global_store_dwordx4 v179, v[20:23], s[6:7]
	global_store_dwordx4 v179, v[8:11], s[6:7] offset:16
	global_store_dwordx4 v179, v[4:7], s[6:7] offset:512
	global_store_dwordx4 v179, v[0:3], s[6:7] offset:528
	s_mov_b32 s18, s12
	s_mov_b64 s[22:23], s[16:17]
	s_mov_b64 s[20:21], s[14:15]
	s_and_b64 vcc, exec, s[2:3]
	s_mov_b32 s1, s10
	s_cbranch_vccz .LBB0_1093
	s_waitcnt vmcnt(0)
	s_cmpk_gt_u32 s29, 0xff
	s_cbranch_scc1 .LBB0_1104
	s_barrier
